# SwiGLU epilogue rewritten by hand: per-element rcp, x=1/rstd^2 folded via pk_fma, no hazard nops; rstd/x read from LDS table
# speedup vs baseline: 1.0223x; 1.0058x over previous
; DI float rss_sum(const float* rss, int row) {
;     const f32x4* p = (const f32x4*)(rss + (size_t)row * 16); const f32x4 a = p[0], b = p[1], c = p[2], d = p[3];
;     return (((a.x + a.y) + (a.z + a.w)) + ((b.x + b.y) + (b.z + b.w))) + (((c.x + c.y) + (c.z + c.w)) + ((d.x + d.y) + (d.z + d.w))); }
; DI void row_rstd8(const float* rss, int row0, int lane, int fq, float (&rs)[8]) {
;     float v[2];
; #pragma unroll
;     for (int e = 0; e < 2; ++e) { const int p = 2 * fq + e; const int row = row0 + (p >> 2) * 128 + (p & 3) * 16; v[e] = 1.0f / sqrtf(rss_sum(rss, row) * (1.0f / DM) + EPS); }
.LBB0_667:
	s_cmp_eq_u32 s58, 2
	s_cbranch_scc0 .Lgu_rs_skip
	s_waitcnt vmcnt(8)
	v_add_f32_e32 v156, v228, v229
	v_add_f32_e32 v157, v230, v231
	v_add_f32_e32 v158, v232, v233
	v_add_f32_e32 v159, v238, v239
	v_add_f32_e32 v156, v156, v157
	v_add_f32_e32 v158, v158, v159
	v_add_f32_e32 v156, v156, v158
	s_nop 1
	v_mov_b32_dpp v157, v156 quad_perm:[1,0,3,2] row_mask:0xf bank_mask:0xf
	s_nop 0
	v_add_f32_e32 v156, v156, v157
	v_fmamk_f32 v156, v156, 0x3a800000, v241
	ds_write_b32 v251, v156 offset:1024
	v_cmp_gt_f32_e32 vcc, s3, v156
	v_mul_f32_e32 v157, 0x4f800000, v156
	s_nop 1
	v_cndmask_b32_e32 v156, v156, v157, vcc
	v_sqrt_f32_e32 v157, v156
	s_nop 0
	v_add_u32_e32 v158, -1, v157
	v_fma_f32 v159, -v158, v157, v156
	v_cmp_ge_f32_e64 s[36:37], 0, v159
	v_add_u32_e32 v159, 1, v157
	s_nop 1
	v_cndmask_b32_e64 v158, v157, v158, s[36:37]
	v_fma_f32 v157, -v159, v157, v156
	v_cmp_lt_f32_e64 s[36:37], 0, v157
	s_nop 1
	v_cndmask_b32_e64 v157, v158, v159, s[36:37]
	v_mul_f32_e32 v158, 0x37800000, v157
	v_cndmask_b32_e32 v157, v157, v158, vcc
	v_cmp_class_f32_e32 vcc, v156, v242
	s_nop 1
	v_cndmask_b32_e32 v156, v157, v156, vcc
	v_div_scale_f32 v157, s[36:37], v156, v156, 1.0
	v_rcp_f32_e32 v158, v157
	s_nop 0
	v_fma_f32 v159, -v157, v158, 1.0
	v_fmac_f32_e32 v158, v159, v158
	v_div_scale_f32 v159, vcc, 1.0, v156, 1.0
	v_mul_f32_e32 v160, v159, v158
	v_fma_f32 v161, -v157, v160, v159
	v_fmac_f32_e32 v160, v161, v158
	v_fma_f32 v157, -v157, v160, v159
	s_nop 0
	v_div_fmas_f32 v157, v157, v158, v160
	v_div_fixup_f32 v156, v157, v156, 1.0
	ds_write_b32 v251, v156

; DI unsigned cvtpk(float lo, float hi) { f32x2_t v = {lo, hi}; bf16x2_t b = __builtin_convertvector(v, bf16x2_t); return __builtin_bit_cast(unsigned, b); }
; DI float fexp2(float x) { return __builtin_amdgcn_exp2f(x); }
; DI float frcp(float x) { return __builtin_amdgcn_rcpf(x); }
;     DI void operator()(const f32x4 (&acc)[2][2][4][2], const Unit& u, int wr, int wc, int fr, int fq) const {
;         const int row0 = u.pm * BM + wr * 64 + fr, col = u.pn * 128 + wc * 32 + 8 * fq;
;         float rs8[8]; row_rstd8(rss, row0, fr + 16 * fq, fq, rs8);
; #pragma unroll
;         for (int ai = 0; ai < 2; ++ai)
; #pragma unroll
;             for (int m = 0; m < 4; ++m) {
;                 const int row = row0 + ai * HALF + m * 16;
;                 const float rstd = rs8[ai * 4 + m];
;                 float hv[8];
; #pragma unroll
;                 for (int n = 0; n < 2; ++n)
; #pragma unroll
;                     for (int j = 0; j < 4; j += 2) {
;                         const float g0 = acc[ai][0][m][n][j] * rstd, u0 = acc[ai][1][m][n][j] * rstd, g1 = acc[ai][0][m][n][j + 1] * rstd, u1 = acc[ai][1][m][n][j + 1] * rstd;
;                         const float d0 = 1.0f + fexp2(fminf(-g0 * LOG2E, 60.0f)), d1 = 1.0f + fexp2(fminf(-g1 * LOG2E, 60.0f));
;                         const float rp = frcp(d0 * d1);
;                         hv[4 * n + j] = g0 * (d1 * rp) * u0; hv[4 * n + j + 1] = g1 * (d0 * rp) * u1;
;                     }
;                 u32x4 w; w.x = cvtpk(hv[0], hv[1]); w.y = cvtpk(hv[2], hv[3]); w.z = cvtpk(hv[4], hv[5]); w.w = cvtpk(hv[6], hv[7]);
;                 *(u32x4*)(H + (size_t)row * FF + col) = w;
;             }
.LBB0_670:
	v_lshl_add_u32 v156, s49, 8, v145
	v_lshl_or_b32 v148, s48, 7, v153
	v_lshlrev_b32_e32 v149, 5, v145
	v_add_u32_e32 v149, 0x20000, v149
	ds_read_b128 v[160:163], v149
	ds_read_b128 v[164:167], v149 offset:16
	ds_read_b128 v[168:171], v149 offset:1024
	ds_read_b128 v[172:175], v149 offset:1040
	v_lshlrev_b32_e32 v148, 1, v148
	v_mad_u32_u24 v150, v156, s77, v148
	v_mov_b32_e32 v140, v150
	v_add_u32_e32 v141, 0x16000, v150
	v_add_u32_e32 v142, 0x2c000, v150
	v_add_u32_e32 v144, 0x42000, v150
	v_add_u32_e32 v146, 0xb0000, v150
	v_add_u32_e32 v152, 0xc6000, v150
	v_add_u32_e32 v154, 0xdc000, v150
	v_add_u32_e32 v158, 0xf2000, v150
	s_waitcnt lgkmcnt(0)
	v_mul_f32_e32 v176, 0xbfb8aa3b, v160
	v_mul_f32_e32 v178, 0xbfb8aa3b, v161
	v_mul_f32_e32 v180, 0xbfb8aa3b, v162
	v_mul_f32_e32 v182, 0xbfb8aa3b, v163
	v_mul_f32_e32 v184, 0xbfb8aa3b, v164
	v_mul_f32_e32 v186, 0xbfb8aa3b, v165
	v_mul_f32_e32 v188, 0xbfb8aa3b, v166
	v_mul_f32_e32 v190, 0xbfb8aa3b, v167
	v_mov_b32_e32 v208, v168
	v_mov_b32_e32 v210, v169
	v_mov_b32_e32 v212, v170
	v_mov_b32_e32 v214, v171
	v_mov_b32_e32 v216, v172
	v_mov_b32_e32 v218, v173
	v_mov_b32_e32 v220, v174
	v_mov_b32_e32 v222, v175
	v_pk_mul_f32 v[192:193], v[126:127], v[176:177] op_sel_hi:[1,0]
	v_pk_mul_f32 v[194:195], v[128:129], v[176:177] op_sel_hi:[1,0]
	v_pk_mul_f32 v[196:197], v[118:119], v[176:177] op_sel_hi:[1,0]
	v_pk_mul_f32 v[198:199], v[120:121], v[176:177] op_sel_hi:[1,0]
	v_exp_f32_e32 v192, v192
	v_exp_f32_e32 v193, v193
	v_exp_f32_e32 v194, v194
	v_exp_f32_e32 v195, v195
	v_exp_f32_e32 v196, v196
	v_exp_f32_e32 v197, v197
	v_exp_f32_e32 v198, v198
	v_exp_f32_e32 v199, v199
	v_pk_mul_f32 v[126:127], v[126:127], v[122:123]
	v_pk_mul_f32 v[128:129], v[128:129], v[124:125]
	v_pk_mul_f32 v[118:119], v[118:119], v[114:115]
	v_pk_mul_f32 v[120:121], v[120:121], v[116:117]
	v_pk_fma_f32 v[192:193], v[192:193], v[208:209], v[208:209] op_sel_hi:[1,0,0]
	v_pk_fma_f32 v[194:195], v[194:195], v[208:209], v[208:209] op_sel_hi:[1,0,0]
	v_pk_fma_f32 v[196:197], v[196:197], v[208:209], v[208:209] op_sel_hi:[1,0,0]
	v_pk_fma_f32 v[198:199], v[198:199], v[208:209], v[208:209] op_sel_hi:[1,0,0]
	v_rcp_f32_e32 v192, v192
	v_rcp_f32_e32 v193, v193
	v_rcp_f32_e32 v194, v194
	v_rcp_f32_e32 v195, v195
	v_rcp_f32_e32 v196, v196
	v_rcp_f32_e32 v197, v197
	v_rcp_f32_e32 v198, v198
	v_rcp_f32_e32 v199, v199
	s_nop 0
	v_pk_mul_f32 v[126:127], v[126:127], v[192:193]
	v_pk_mul_f32 v[128:129], v[128:129], v[194:195]
	v_pk_mul_f32 v[118:119], v[118:119], v[196:197]
	v_pk_mul_f32 v[120:121], v[120:121], v[198:199]
	v_cvt_pk_bf16_f32 v122, v126, v127
	v_cvt_pk_bf16_f32 v123, v128, v129
	v_cvt_pk_bf16_f32 v124, v118, v119
	v_cvt_pk_bf16_f32 v125, v120, v121
	global_store_dwordx4 v140, v[122:125], s[74:75]
	v_pk_mul_f32 v[192:193], v[110:111], v[178:179] op_sel_hi:[1,0]
	v_pk_mul_f32 v[194:195], v[112:113], v[178:179] op_sel_hi:[1,0]
	v_pk_mul_f32 v[196:197], v[102:103], v[178:179] op_sel_hi:[1,0]
	v_pk_mul_f32 v[198:199], v[104:105], v[178:179] op_sel_hi:[1,0]
	v_exp_f32_e32 v192, v192
	v_exp_f32_e32 v193, v193
	v_exp_f32_e32 v194, v194
	v_exp_f32_e32 v195, v195
	v_exp_f32_e32 v196, v196
	v_exp_f32_e32 v197, v197
	v_exp_f32_e32 v198, v198
	v_exp_f32_e32 v199, v199
	v_pk_mul_f32 v[110:111], v[110:111], v[106:107]
	v_pk_mul_f32 v[112:113], v[112:113], v[108:109]
	v_pk_mul_f32 v[102:103], v[102:103], v[98:99]
	v_pk_mul_f32 v[104:105], v[104:105], v[100:101]
	v_pk_fma_f32 v[192:193], v[192:193], v[210:211], v[210:211] op_sel_hi:[1,0,0]
	v_pk_fma_f32 v[194:195], v[194:195], v[210:211], v[210:211] op_sel_hi:[1,0,0]
	v_pk_fma_f32 v[196:197], v[196:197], v[210:211], v[210:211] op_sel_hi:[1,0,0]
	v_pk_fma_f32 v[198:199], v[198:199], v[210:211], v[210:211] op_sel_hi:[1,0,0]
	v_rcp_f32_e32 v192, v192
	v_rcp_f32_e32 v193, v193
	v_rcp_f32_e32 v194, v194
	v_rcp_f32_e32 v195, v195
	v_rcp_f32_e32 v196, v196
	v_rcp_f32_e32 v197, v197
	v_rcp_f32_e32 v198, v198
	v_rcp_f32_e32 v199, v199
	s_nop 0
	v_pk_mul_f32 v[110:111], v[110:111], v[192:193]
	v_pk_mul_f32 v[112:113], v[112:113], v[194:195]
	v_pk_mul_f32 v[102:103], v[102:103], v[196:197]
	v_pk_mul_f32 v[104:105], v[104:105], v[198:199]
	v_cvt_pk_bf16_f32 v106, v110, v111
	v_cvt_pk_bf16_f32 v107, v112, v113
	v_cvt_pk_bf16_f32 v108, v102, v103
	v_cvt_pk_bf16_f32 v109, v104, v105
	global_store_dwordx4 v141, v[106:109], s[74:75]
	v_pk_mul_f32 v[192:193], v[94:95], v[180:181] op_sel_hi:[1,0]
	v_pk_mul_f32 v[194:195], v[96:97], v[180:181] op_sel_hi:[1,0]
	v_pk_mul_f32 v[196:197], v[86:87], v[180:181] op_sel_hi:[1,0]
	v_pk_mul_f32 v[198:199], v[88:89], v[180:181] op_sel_hi:[1,0]
	v_exp_f32_e32 v192, v192
	v_exp_f32_e32 v193, v193
	v_exp_f32_e32 v194, v194
	v_exp_f32_e32 v195, v195
	v_exp_f32_e32 v196, v196
	v_exp_f32_e32 v197, v197
	v_exp_f32_e32 v198, v198
	v_exp_f32_e32 v199, v199
	v_pk_mul_f32 v[94:95], v[94:95], v[90:91]
	v_pk_mul_f32 v[96:97], v[96:97], v[92:93]
	v_pk_mul_f32 v[86:87], v[86:87], v[82:83]
	v_pk_mul_f32 v[88:89], v[88:89], v[84:85]
	v_pk_fma_f32 v[192:193], v[192:193], v[212:213], v[212:213] op_sel_hi:[1,0,0]
	v_pk_fma_f32 v[194:195], v[194:195], v[212:213], v[212:213] op_sel_hi:[1,0,0]
	v_pk_fma_f32 v[196:197], v[196:197], v[212:213], v[212:213] op_sel_hi:[1,0,0]
	v_pk_fma_f32 v[198:199], v[198:199], v[212:213], v[212:213] op_sel_hi:[1,0,0]
	v_rcp_f32_e32 v192, v192
	v_rcp_f32_e32 v193, v193
	v_rcp_f32_e32 v194, v194
	v_rcp_f32_e32 v195, v195
	v_rcp_f32_e32 v196, v196
	v_rcp_f32_e32 v197, v197
	v_rcp_f32_e32 v198, v198
	v_rcp_f32_e32 v199, v199
	s_nop 0
	v_pk_mul_f32 v[94:95], v[94:95], v[192:193]
	v_pk_mul_f32 v[96:97], v[96:97], v[194:195]
	v_pk_mul_f32 v[86:87], v[86:87], v[196:197]
; DI unsigned cvtpk(float lo, float hi) { f32x2_t v = {lo, hi}; bf16x2_t b = __builtin_convertvector(v, bf16x2_t); return __builtin_bit_cast(unsigned, b); }
; DI float fexp2(float x) { return __builtin_amdgcn_exp2f(x); }
; DI float frcp(float x) { return __builtin_amdgcn_rcpf(x); }
;     DI void operator()(const f32x4 (&acc)[2][2][4][2], const Unit& u, int wr, int wc, int fr, int fq) const {
;         const int row0 = u.pm * BM + wr * 64 + fr, col = u.pn * 128 + wc * 32 + 8 * fq;
;         float rs8[8]; row_rstd8(rss, row0, fr + 16 * fq, fq, rs8);
; #pragma unroll
;         for (int ai = 0; ai < 2; ++ai)
; #pragma unroll
;             for (int m = 0; m < 4; ++m) {
;                 const int row = row0 + ai * HALF + m * 16;
;                 const float rstd = rs8[ai * 4 + m];
;                 float hv[8];
; #pragma unroll
;                 for (int n = 0; n < 2; ++n)
; #pragma unroll
;                     for (int j = 0; j < 4; j += 2) {
;                         const float g0 = acc[ai][0][m][n][j] * rstd, u0 = acc[ai][1][m][n][j] * rstd, g1 = acc[ai][0][m][n][j + 1] * rstd, u1 = acc[ai][1][m][n][j + 1] * rstd;
;                         const float d0 = 1.0f + fexp2(fminf(-g0 * LOG2E, 60.0f)), d1 = 1.0f + fexp2(fminf(-g1 * LOG2E, 60.0f));
;                         const float rp = frcp(d0 * d1);
;                         hv[4 * n + j] = g0 * (d1 * rp) * u0; hv[4 * n + j + 1] = g1 * (d0 * rp) * u1;
;                     }
;                 u32x4 w; w.x = cvtpk(hv[0], hv[1]); w.y = cvtpk(hv[2], hv[3]); w.z = cvtpk(hv[4], hv[5]); w.w = cvtpk(hv[6], hv[7]);
;                 *(u32x4*)(H + (size_t)row * FF + col) = w;
;             }
	v_pk_mul_f32 v[88:89], v[88:89], v[198:199]
	v_cvt_pk_bf16_f32 v90, v94, v95
	v_cvt_pk_bf16_f32 v91, v96, v97
	v_cvt_pk_bf16_f32 v92, v86, v87
	v_cvt_pk_bf16_f32 v93, v88, v89
	global_store_dwordx4 v142, v[90:93], s[74:75]
	v_pk_mul_f32 v[192:193], v[78:79], v[182:183] op_sel_hi:[1,0]
	v_pk_mul_f32 v[194:195], v[80:81], v[182:183] op_sel_hi:[1,0]
	v_pk_mul_f32 v[196:197], v[70:71], v[182:183] op_sel_hi:[1,0]
	v_pk_mul_f32 v[198:199], v[72:73], v[182:183] op_sel_hi:[1,0]
	v_exp_f32_e32 v192, v192
	v_exp_f32_e32 v193, v193
	v_exp_f32_e32 v194, v194
	v_exp_f32_e32 v195, v195
	v_exp_f32_e32 v196, v196
	v_exp_f32_e32 v197, v197
	v_exp_f32_e32 v198, v198
	v_exp_f32_e32 v199, v199
	v_pk_mul_f32 v[78:79], v[78:79], v[74:75]
	v_pk_mul_f32 v[80:81], v[80:81], v[76:77]
	v_pk_mul_f32 v[70:71], v[70:71], v[66:67]
	v_pk_mul_f32 v[72:73], v[72:73], v[68:69]
	v_pk_fma_f32 v[192:193], v[192:193], v[214:215], v[214:215] op_sel_hi:[1,0,0]
	v_pk_fma_f32 v[194:195], v[194:195], v[214:215], v[214:215] op_sel_hi:[1,0,0]
	v_pk_fma_f32 v[196:197], v[196:197], v[214:215], v[214:215] op_sel_hi:[1,0,0]
	v_pk_fma_f32 v[198:199], v[198:199], v[214:215], v[214:215] op_sel_hi:[1,0,0]
	v_rcp_f32_e32 v192, v192
	v_rcp_f32_e32 v193, v193
	v_rcp_f32_e32 v194, v194
	v_rcp_f32_e32 v195, v195
	v_rcp_f32_e32 v196, v196
	v_rcp_f32_e32 v197, v197
	v_rcp_f32_e32 v198, v198
	v_rcp_f32_e32 v199, v199
	s_nop 0
	v_pk_mul_f32 v[78:79], v[78:79], v[192:193]
	v_pk_mul_f32 v[80:81], v[80:81], v[194:195]
	v_pk_mul_f32 v[70:71], v[70:71], v[196:197]
	v_pk_mul_f32 v[72:73], v[72:73], v[198:199]
	v_cvt_pk_bf16_f32 v74, v78, v79
	v_cvt_pk_bf16_f32 v75, v80, v81
	v_cvt_pk_bf16_f32 v76, v70, v71
	v_cvt_pk_bf16_f32 v77, v72, v73
	global_store_dwordx4 v144, v[74:77], s[74:75]
	v_pk_mul_f32 v[192:193], v[62:63], v[184:185] op_sel_hi:[1,0]
	v_pk_mul_f32 v[194:195], v[64:65], v[184:185] op_sel_hi:[1,0]
	v_pk_mul_f32 v[196:197], v[54:55], v[184:185] op_sel_hi:[1,0]
	v_pk_mul_f32 v[198:199], v[56:57], v[184:185] op_sel_hi:[1,0]
	v_exp_f32_e32 v192, v192
	v_exp_f32_e32 v193, v193
	v_exp_f32_e32 v194, v194
	v_exp_f32_e32 v195, v195
	v_exp_f32_e32 v196, v196
	v_exp_f32_e32 v197, v197
	v_exp_f32_e32 v198, v198
	v_exp_f32_e32 v199, v199
	v_pk_mul_f32 v[62:63], v[62:63], v[58:59]
	v_pk_mul_f32 v[64:65], v[64:65], v[60:61]
	v_pk_mul_f32 v[54:55], v[54:55], v[50:51]
	v_pk_mul_f32 v[56:57], v[56:57], v[52:53]
	v_pk_fma_f32 v[192:193], v[192:193], v[216:217], v[216:217] op_sel_hi:[1,0,0]
	v_pk_fma_f32 v[194:195], v[194:195], v[216:217], v[216:217] op_sel_hi:[1,0,0]
	v_pk_fma_f32 v[196:197], v[196:197], v[216:217], v[216:217] op_sel_hi:[1,0,0]
	v_pk_fma_f32 v[198:199], v[198:199], v[216:217], v[216:217] op_sel_hi:[1,0,0]
	v_rcp_f32_e32 v192, v192
	v_rcp_f32_e32 v193, v193
	v_rcp_f32_e32 v194, v194
	v_rcp_f32_e32 v195, v195
	v_rcp_f32_e32 v196, v196
	v_rcp_f32_e32 v197, v197
	v_rcp_f32_e32 v198, v198
	v_rcp_f32_e32 v199, v199
	s_nop 0
	v_pk_mul_f32 v[62:63], v[62:63], v[192:193]
	v_pk_mul_f32 v[64:65], v[64:65], v[194:195]
	v_pk_mul_f32 v[54:55], v[54:55], v[196:197]
	v_pk_mul_f32 v[56:57], v[56:57], v[198:199]
	v_cvt_pk_bf16_f32 v58, v62, v63
	v_cvt_pk_bf16_f32 v59, v64, v65
	v_cvt_pk_bf16_f32 v60, v54, v55
	v_cvt_pk_bf16_f32 v61, v56, v57
	global_store_dwordx4 v146, v[58:61], s[74:75]
	v_pk_mul_f32 v[192:193], v[46:47], v[186:187] op_sel_hi:[1,0]
	v_pk_mul_f32 v[194:195], v[48:49], v[186:187] op_sel_hi:[1,0]
	v_pk_mul_f32 v[196:197], v[38:39], v[186:187] op_sel_hi:[1,0]
	v_pk_mul_f32 v[198:199], v[40:41], v[186:187] op_sel_hi:[1,0]
	v_exp_f32_e32 v192, v192
	v_exp_f32_e32 v193, v193
	v_exp_f32_e32 v194, v194
	v_exp_f32_e32 v195, v195
	v_exp_f32_e32 v196, v196
	v_exp_f32_e32 v197, v197
	v_exp_f32_e32 v198, v198
	v_exp_f32_e32 v199, v199
	v_pk_mul_f32 v[46:47], v[46:47], v[42:43]
	v_pk_mul_f32 v[48:49], v[48:49], v[44:45]
	v_pk_mul_f32 v[38:39], v[38:39], v[34:35]
	v_pk_mul_f32 v[40:41], v[40:41], v[36:37]
	v_pk_fma_f32 v[192:193], v[192:193], v[218:219], v[218:219] op_sel_hi:[1,0,0]
; DI unsigned cvtpk(float lo, float hi) { f32x2_t v = {lo, hi}; bf16x2_t b = __builtin_convertvector(v, bf16x2_t); return __builtin_bit_cast(unsigned, b); }
; DI float fexp2(float x) { return __builtin_amdgcn_exp2f(x); }
; DI float frcp(float x) { return __builtin_amdgcn_rcpf(x); }
;     DI void operator()(const f32x4 (&acc)[2][2][4][2], const Unit& u, int wr, int wc, int fr, int fq) const {
;         const int row0 = u.pm * BM + wr * 64 + fr, col = u.pn * 128 + wc * 32 + 8 * fq;
;         float rs8[8]; row_rstd8(rss, row0, fr + 16 * fq, fq, rs8);
; #pragma unroll
;         for (int ai = 0; ai < 2; ++ai)
; #pragma unroll
;             for (int m = 0; m < 4; ++m) {
;                 const int row = row0 + ai * HALF + m * 16;
;                 const float rstd = rs8[ai * 4 + m];
;                 float hv[8];
; #pragma unroll
;                 for (int n = 0; n < 2; ++n)
; #pragma unroll
;                     for (int j = 0; j < 4; j += 2) {
;                         const float g0 = acc[ai][0][m][n][j] * rstd, u0 = acc[ai][1][m][n][j] * rstd, g1 = acc[ai][0][m][n][j + 1] * rstd, u1 = acc[ai][1][m][n][j + 1] * rstd;
;                         const float d0 = 1.0f + fexp2(fminf(-g0 * LOG2E, 60.0f)), d1 = 1.0f + fexp2(fminf(-g1 * LOG2E, 60.0f));
;                         const float rp = frcp(d0 * d1);
;                         hv[4 * n + j] = g0 * (d1 * rp) * u0; hv[4 * n + j + 1] = g1 * (d0 * rp) * u1;
;                     }
;                 u32x4 w; w.x = cvtpk(hv[0], hv[1]); w.y = cvtpk(hv[2], hv[3]); w.z = cvtpk(hv[4], hv[5]); w.w = cvtpk(hv[6], hv[7]);
;                 *(u32x4*)(H + (size_t)row * FF + col) = w;
;             }
	v_pk_fma_f32 v[194:195], v[194:195], v[218:219], v[218:219] op_sel_hi:[1,0,0]
	v_pk_fma_f32 v[196:197], v[196:197], v[218:219], v[218:219] op_sel_hi:[1,0,0]
	v_pk_fma_f32 v[198:199], v[198:199], v[218:219], v[218:219] op_sel_hi:[1,0,0]
	v_rcp_f32_e32 v192, v192
	v_rcp_f32_e32 v193, v193
	v_rcp_f32_e32 v194, v194
	v_rcp_f32_e32 v195, v195
	v_rcp_f32_e32 v196, v196
	v_rcp_f32_e32 v197, v197
	v_rcp_f32_e32 v198, v198
	v_rcp_f32_e32 v199, v199
	s_nop 0
	v_pk_mul_f32 v[46:47], v[46:47], v[192:193]
	v_pk_mul_f32 v[48:49], v[48:49], v[194:195]
	v_pk_mul_f32 v[38:39], v[38:39], v[196:197]
	v_pk_mul_f32 v[40:41], v[40:41], v[198:199]
	v_cvt_pk_bf16_f32 v42, v46, v47
	v_cvt_pk_bf16_f32 v43, v48, v49
	v_cvt_pk_bf16_f32 v44, v38, v39
	v_cvt_pk_bf16_f32 v45, v40, v41
	global_store_dwordx4 v152, v[42:45], s[74:75]
	v_pk_mul_f32 v[192:193], v[30:31], v[188:189] op_sel_hi:[1,0]
	v_pk_mul_f32 v[194:195], v[32:33], v[188:189] op_sel_hi:[1,0]
	v_pk_mul_f32 v[196:197], v[22:23], v[188:189] op_sel_hi:[1,0]
	v_pk_mul_f32 v[198:199], v[24:25], v[188:189] op_sel_hi:[1,0]
	v_exp_f32_e32 v192, v192
	v_exp_f32_e32 v193, v193
	v_exp_f32_e32 v194, v194
	v_exp_f32_e32 v195, v195
	v_exp_f32_e32 v196, v196
	v_exp_f32_e32 v197, v197
	v_exp_f32_e32 v198, v198
	v_exp_f32_e32 v199, v199
	v_pk_mul_f32 v[30:31], v[30:31], v[26:27]
	v_pk_mul_f32 v[32:33], v[32:33], v[28:29]
	v_pk_mul_f32 v[22:23], v[22:23], v[18:19]
	v_pk_mul_f32 v[24:25], v[24:25], v[20:21]
	v_pk_fma_f32 v[192:193], v[192:193], v[220:221], v[220:221] op_sel_hi:[1,0,0]
	v_pk_fma_f32 v[194:195], v[194:195], v[220:221], v[220:221] op_sel_hi:[1,0,0]
	v_pk_fma_f32 v[196:197], v[196:197], v[220:221], v[220:221] op_sel_hi:[1,0,0]
	v_pk_fma_f32 v[198:199], v[198:199], v[220:221], v[220:221] op_sel_hi:[1,0,0]
	v_rcp_f32_e32 v192, v192
	v_rcp_f32_e32 v193, v193
	v_rcp_f32_e32 v194, v194
	v_rcp_f32_e32 v195, v195
	v_rcp_f32_e32 v196, v196
	v_rcp_f32_e32 v197, v197
	v_rcp_f32_e32 v198, v198
	v_rcp_f32_e32 v199, v199
	s_nop 0
	v_pk_mul_f32 v[30:31], v[30:31], v[192:193]
	v_pk_mul_f32 v[32:33], v[32:33], v[194:195]
	v_pk_mul_f32 v[22:23], v[22:23], v[196:197]
	v_pk_mul_f32 v[24:25], v[24:25], v[198:199]
	v_cvt_pk_bf16_f32 v26, v30, v31
	v_cvt_pk_bf16_f32 v27, v32, v33
	v_cvt_pk_bf16_f32 v28, v22, v23
	v_cvt_pk_bf16_f32 v29, v24, v25
	global_store_dwordx4 v154, v[26:29], s[74:75]
	v_pk_mul_f32 v[192:193], v[14:15], v[190:191] op_sel_hi:[1,0]
	v_pk_mul_f32 v[194:195], v[16:17], v[190:191] op_sel_hi:[1,0]
	v_pk_mul_f32 v[196:197], v[6:7], v[190:191] op_sel_hi:[1,0]
	v_pk_mul_f32 v[198:199], v[8:9], v[190:191] op_sel_hi:[1,0]
	v_exp_f32_e32 v192, v192
	v_exp_f32_e32 v193, v193
	v_exp_f32_e32 v194, v194
	v_exp_f32_e32 v195, v195
	v_exp_f32_e32 v196, v196
	v_exp_f32_e32 v197, v197
	v_exp_f32_e32 v198, v198
	v_exp_f32_e32 v199, v199
	v_pk_mul_f32 v[14:15], v[14:15], v[10:11]
	v_pk_mul_f32 v[16:17], v[16:17], v[12:13]
	v_pk_mul_f32 v[6:7], v[6:7], v[2:3]
	v_pk_mul_f32 v[8:9], v[8:9], v[4:5]
	v_pk_fma_f32 v[192:193], v[192:193], v[222:223], v[222:223] op_sel_hi:[1,0,0]
	v_pk_fma_f32 v[194:195], v[194:195], v[222:223], v[222:223] op_sel_hi:[1,0,0]
	v_pk_fma_f32 v[196:197], v[196:197], v[222:223], v[222:223] op_sel_hi:[1,0,0]
	v_pk_fma_f32 v[198:199], v[198:199], v[222:223], v[222:223] op_sel_hi:[1,0,0]
	v_rcp_f32_e32 v192, v192
	v_rcp_f32_e32 v193, v193
	v_rcp_f32_e32 v194, v194
	v_rcp_f32_e32 v195, v195
	v_rcp_f32_e32 v196, v196
	v_rcp_f32_e32 v197, v197
	v_rcp_f32_e32 v198, v198
	v_rcp_f32_e32 v199, v199
	s_nop 0
	v_pk_mul_f32 v[14:15], v[14:15], v[192:193]
	v_pk_mul_f32 v[16:17], v[16:17], v[194:195]
	v_pk_mul_f32 v[6:7], v[6:7], v[196:197]
	v_pk_mul_f32 v[8:9], v[8:9], v[198:199]
	v_cvt_pk_bf16_f32 v10, v14, v15
	v_cvt_pk_bf16_f32 v11, v16, v17
	v_cvt_pk_bf16_f32 v12, v6, v7
	v_cvt_pk_bf16_f32 v13, v8, v9
	global_store_dwordx4 v158, v[10:13], s[74:75]
	s_andn2_b64 vcc, exec, s[4:5]
	s_mov_b64 s[6:7], -1
	s_cbranch_vccnz .LBB0_663
	s_andn2_b64 vcc, exec, s[0:1]
	s_cbranch_vccnz .LBB0_662
	s_barrier
	s_branch .LBB0_662
